# P5: odd workgroups run the mLSTM scan before attention, even after (scan overlaps attention)
# speedup vs baseline: 1.0147x; 1.0026x over previous
.LBB0_670:
	v_writelane_b32 v255, s64, 53
	s_cmpk_gt_i32 s16, 0xff
	v_mbcnt_lo_u32_b32 v0, -1, 0
	v_mbcnt_hi_u32_b32 v0, -1, v0
	s_cbranch_scc1 .LBB0_711
	s_bitcmp1_b32 s64, 0
	s_cbranch_scc0 .Lp5_attn_entry
	s_cmp_eq_u32 s98, 0x52
	s_cbranch_scc1 .Lp5_attn_entry
	s_mov_b32 s98, 0x51
	s_mov_b32 s99, s16
	v_readlane_b32 s73, v254, 20
	s_branch .LBB0_711
.Lp5_attn_entry:
	v_readlane_b32 s0, v255, 28
	v_readlane_b32 s14, v255, 42
	v_readlane_b32 s1, v255, 29
	v_readlane_b32 s15, v255, 43
	s_add_u32 s0, s14, 0x2a01000
	s_addc_u32 s1, s15, 0
	v_readlane_b32 s2, v255, 30
	v_readlane_b32 s3, v255, 31
	v_readlane_b32 s4, v255, 32
	v_readlane_b32 s5, v255, 33
	v_readlane_b32 s6, v255, 34
	v_readlane_b32 s7, v255, 35
	v_readlane_b32 s8, v255, 36
	v_readlane_b32 s9, v255, 37
	v_readlane_b32 s10, v255, 38
	v_readlane_b32 s11, v255, 39
	v_readlane_b32 s12, v255, 40
	v_readlane_b32 s13, v255, 41
	v_writelane_b32 v255, s0, 54
	v_mbcnt_lo_u32_b32 v1, -1, 0
	v_and_b32_e32 v227, 63, v0
	v_writelane_b32 v255, s1, 55
	s_add_u32 s0, s14, 0x13002000
	s_addc_u32 s1, s15, 0
	v_writelane_b32 v255, s0, 56
	v_mov_b32_e32 v225, 0
	s_mov_b32 s72, 0x41000000
	v_writelane_b32 v255, s1, 57
	s_add_u32 s0, s14, 0x15002000
	s_addc_u32 s1, s15, 0
	v_writelane_b32 v255, s0, 58
	s_mov_b64 s[76:77], 0x2000
	v_mov_b32_e32 v0, 0xff800000
	v_writelane_b32 v255, s1, 59
	v_writelane_b32 v255, s90, 60
	v_mbcnt_hi_u32_b32 v234, -1, v1
	v_mov_b32_e32 v226, 0x358637bd
	v_writelane_b32 v255, s91, 61
	s_branch .LBB0_673

.LBB0_711:
	v_readlane_b32 s0, v255, 28
	v_readlane_b32 s14, v255, 42
	v_readlane_b32 s15, v255, 43
	v_readlane_b32 s57, v255, 53
	v_readlane_b32 s2, v255, 30
	v_readlane_b32 s3, v255, 31
	v_readlane_b32 s10, v255, 38
	v_readlane_b32 s11, v255, 39
	v_readlane_b32 s12, v255, 40
	v_readlane_b32 s13, v255, 41
	s_mov_b64 s[70:71], s[14:15]
	v_readlane_b32 s60, v255, 26
	v_readlane_b32 s62, v255, 24
	v_readlane_b32 s64, v255, 21
	v_readlane_b32 s36, v254, 31
	s_cmpk_gt_i32 s57, 0xff
	s_mov_b64 s[68:69], s[12:13]
	s_mov_b64 s[58:59], s[2:3]
	s_mov_b64 s[66:67], s[10:11]
	v_readlane_b32 s61, v255, 27
	v_readlane_b32 s63, v255, 25
	v_readlane_b32 s65, v255, 22
	v_readlane_b32 s56, v255, 20
	v_readlane_b32 s88, v255, 19
	v_readlane_b32 s89, v255, 18
	v_readlane_b32 s50, v254, 45
	v_readlane_b32 s51, v254, 46
	v_mbcnt_lo_u32_b32 v0, -1, 0
	v_mbcnt_hi_u32_b32 v0, -1, v0
	v_readlane_b32 s1, v255, 29
	v_readlane_b32 s4, v255, 32
	v_readlane_b32 s5, v255, 33
	v_readlane_b32 s6, v255, 34
	v_readlane_b32 s7, v255, 35
	v_readlane_b32 s8, v255, 36
	v_readlane_b32 s9, v255, 37
	v_readlane_b32 s37, v254, 32
	v_readlane_b32 s38, v254, 33
	v_readlane_b32 s39, v254, 34
	v_readlane_b32 s40, v254, 35
	v_readlane_b32 s41, v254, 36
	v_readlane_b32 s42, v254, 37
	v_readlane_b32 s43, v254, 38
	v_readlane_b32 s44, v254, 39
	v_readlane_b32 s45, v254, 40
	v_readlane_b32 s46, v254, 41
	v_readlane_b32 s47, v254, 42
	v_readlane_b32 s48, v254, 43
	v_readlane_b32 s49, v254, 44
	s_cbranch_scc1 .LBB0_796
	s_cmp_eq_u32 s98, 0x52
	s_cbranch_scc1 .LBB0_796
	v_and_b32_e32 v0, 63, v0
	v_readlane_b32 s0, v254, 19
	v_mov_b32_e32 v80, 0x700000
	v_mov_b32_e32 v81, 0x710000
	v_or_b32_e32 v78, s0, v0
	v_add_u32_e32 v79, s0, v0
	v_mov_b32_e32 v82, 0x720000
	s_mov_b64 s[2:3], 0x40000
	s_mov_b64 s[4:5], 0x1000
	s_mov_b64 s[8:9], 0x80000
	s_branch .LBB0_714

.LBB0_796:
	s_cmp_eq_u32 s98, 0x51
	s_cbranch_scc0 .Lp5_scan_done
	s_mov_b32 s98, 0x52
	s_mov_b64 exec, -1
	s_mov_b32 s16, s99
	v_mbcnt_lo_u32_b32 v0, -1, 0
	v_mbcnt_hi_u32_b32 v0, -1, v0
	s_branch .Lp5_attn_entry
